# static prio: GEMM K-loops waves 4-7, scan2 waves 0-3 (the MFMA chain waves); first-barrier census loads de-serialized
# speedup vs baseline: 1.0053x; 1.0053x over previous
; __device__ __forceinline__ unsigned xb_ld(unsigned* p)              { return __hip_atomic_load(p, __ATOMIC_RELAXED, __HIP_MEMORY_SCOPE_AGENT); }
; __device__ __forceinline__ void xcd_barrier_complete(unsigned* bar, unsigned x, unsigned& nloc, unsigned& nx) {
;     const unsigned G = gridDim.x * gridDim.y * gridDim.z;
;     unsigned sum, cnt, mine, sp = 0u;
;     for (;;) {
;         sum = 0u; cnt = 0u; mine = 0u;
; #pragma unroll
;         for (unsigned j = 0; j < 16; ++j) { const unsigned c = xb_ld(&bar[XB_XCNT(j)]); sum += c; cnt += (c > 0u) ? 1u : 0u; mine = (j == x) ? c : mine; }
;         if (sum == G) break;
;         __builtin_amdgcn_s_sleep(1);
;         if ((++sp & 255u) == 0u) { if (xb_ld(&bar[XB_TMO])) break; if (sp > XB_SPIN_CAP) { atomicAdd(&bar[XB_TMO], 1u); break; } }
;     }
.LBB0_215:
	v_mov_b64_e32 v[20:21], s[52:53]
	flat_load_dword v2, v[20:21] offset:1024 sc1
	flat_load_dword v0, v[20:21] offset:1280 sc1
	flat_load_dword v3, v[20:21] offset:1536 sc1
	flat_load_dword v4, v[20:21] offset:1792 sc1
	flat_load_dword v5, v[20:21] offset:2048 sc1
	flat_load_dword v6, v[20:21] offset:2304 sc1
	flat_load_dword v7, v[20:21] offset:2560 sc1
	flat_load_dword v8, v[20:21] offset:2816 sc1
	flat_load_dword v9, v[20:21] offset:3072 sc1
	flat_load_dword v10, v[20:21] offset:3328 sc1
	flat_load_dword v11, v[20:21] offset:3584 sc1
	flat_load_dword v12, v[20:21] offset:3840 sc1
	v_mov_b64_e32 v[22:23], s[6:7]
	flat_load_dword v13, v[22:23] sc1
	v_mov_b64_e32 v[22:23], s[8:9]
	flat_load_dword v14, v[22:23] sc1
	v_mov_b64_e32 v[22:23], s[10:11]
	flat_load_dword v15, v[22:23] sc1
	v_mov_b64_e32 v[22:23], s[12:13]
	flat_load_dword v16, v[22:23] sc1
	s_or_b64 s[20:21], s[20:21], exec
	s_or_b64 s[18:19], s[18:19], exec
	s_waitcnt vmcnt(0) lgkmcnt(0)
	v_add3_u32 v17, v0, v2, v3
	v_add3_u32 v17, v17, v4, v5
	v_add3_u32 v17, v17, v6, v7
	v_add3_u32 v17, v17, v8, v9
	v_add3_u32 v17, v17, v10, v11
	v_add3_u32 v17, v17, v12, v13
	v_add3_u32 v17, v17, v14, v15
	v_add_u32_e32 v17, v17, v16
	v_cmp_ne_u32_e32 vcc, s34, v17
	s_and_saveexec_b64 s[22:23], vcc
	s_cbranch_execz .LBB0_214
	s_and_b32 s26, s35, 0xff
	s_mov_b64 s[24:25], -1
	s_cmp_eq_u32 s26, 0
	s_mov_b64 s[28:29], -1
	s_mov_b64 s[26:27], -1
	s_sleep 1
	s_cbranch_scc1 .LBB0_218
	s_and_saveexec_b64 s[30:31], s[28:29]
	s_cbranch_execz .LBB0_213
	s_branch .LBB0_221

; __device__ __forceinline__ int lane_id_asm() { int v; asm volatile("v_mbcnt_lo_u32_b32 %0, -1, 0\n\tv_mbcnt_hi_u32_b32 %0, -1, %0" : "=v"(v)); return v; }
; #define GAS __attribute__((address_space(1)))
; #define LAS __attribute__((address_space(3)))
; __device__ __forceinline__ kptr_t kargs() { kptr_t p = (kptr_t)__builtin_amdgcn_kernarg_segment_ptr(); asm volatile("" : "+s"(p)); return p; }
; template <class T> __device__ __forceinline__ T* launder_s(T* p) { asm volatile("" : "+s"(p)); return p; }
; template <class T> __device__ __forceinline__ LAS T* launder_l(LAS T* p) { asm volatile("" : "+v"(p)); return p; }
; __device__ __forceinline__ void phase_scan2(Frame& F, int l) {
;     const kptr_t ka = kargs(); const int lane = lane_id_asm(), tid = F.wave * 64 + lane; (void)ka;
;     unsigned char* const ws_ = launder_s(F.ws); float* const out_ = launder_s(F.out);
;     LAS bf16* MT = launder_l((LAS bf16*)(F.lds + RING_OFF));
;     LAS float* NB = (LAS float*)(MT + 2 * 64 * CP);
;     LAS bf16* SH = (LAS bf16*)(NB + 2 * 1024);
;     LAS bf16* SL = SH + 16 * CP;
;     const GAS bf16* WDb = (const GAS bf16*)(ws_ + WS_WD); const GAS bf16* AAb = (const GAS bf16*)(ws_ + WS_AA); GAS bf16* SC = (GAS bf16*)(ws_ + WS_HB);
;     const int G = F.G, w = F.wave, fr = lane & 15, fq = lane >> 4;
;     const int mrow = tid >> 3, mc8 = (tid & 7) * 8;
;     constexpr int NPI = BP * NH * 4, NSI = BS * NH * 4;
;     for (int item = F.vcu; item < NPI + NSI; item += G) {
;         const bool samp = item >= NPI; const int q = samp ? item - NPI : item, seq = q >> 2, rq = q & 3, b = seq >> 4, h = seq & 15;
;         const int nch = samp ? 1 : TP / 64, cidx0 = samp ? BP * NH * 64 + seq : seq * 64, m0 = samp ? MP + b * TS : b * TP;
;         f32x4 sD = {0.f, 0.f, 0.f, 0.f};
.LBB0_630:
	s_andn2_b64 vcc, exec, s[6:7]
	s_cbranch_vccnz .LBB0_762
	s_cmp_lt_u32 s47, 4
	s_cbranch_scc0 .Lpp_skip_scan2
	s_setprio 1
.Lpp_skip_scan2:
	v_readlane_b32 s0, v254, 0
	v_readlane_b32 s1, v254, 1
	s_load_dwordx4 s[16:19], s[0:1], 0xd0
	s_mov_b64 s[12:13], s[0:1]
	v_readlane_b32 s0, v254, 38
	v_readlane_b32 s1, v254, 39
	s_mov_b32 s8, s91
	s_waitcnt lgkmcnt(0)
	s_mov_b64 s[20:21], s[18:19]
	s_mov_b64 s[10:11], s[16:17]
	s_waitcnt vmcnt(0)
	v_mov_b32_e32 v2, v1
	s_andn2_b64 vcc, exec, s[0:1]
	v_mbcnt_lo_u32_b32 v3, -1, 0
	v_mbcnt_hi_u32_b32 v3, -1, v3
	s_cbranch_vccnz .LBB0_714
	s_add_u32 s14, s20, 0x43ba0000
	s_addc_u32 s15, s21, 0
	s_add_u32 s16, s20, 0x47fa0000
	v_readlane_b32 s0, v254, 14
	s_addc_u32 s17, s21, 0
	v_lshlrev_b32_e32 v0, 3, v3
	v_add_u32_e32 v8, s0, v3
	s_ashr_i32 s9, s8, 31
	s_movk_i32 s0, 0x80
	v_and_b32_e32 v40, 56, v0
	v_ashrrev_i32_e32 v42, 3, v8
	s_lshl_b64 s[18:19], s[8:9], 8
	v_cmp_gt_i32_e64 s[6:7], s0, v8
	s_lshl_b32 s0, s96, 1
	v_lshl_add_u32 v5, v40, 2, v2
	v_lshlrev_b32_e32 v0, 1, v40
	v_and_b32_e32 v4, 15, v3
	v_mul_lo_u32 v9, v42, s86
	s_add_u32 s0, s20, s0
	v_sub_u32_e32 v7, v5, v0
	v_or_b32_e32 v6, s96, v4
	v_lshl_add_u64 v[46:47], s[14:15], 0, v[0:1]
	v_add3_u32 v64, v2, v9, v0
	v_lshl_add_u64 v[48:49], s[16:17], 0, v[0:1]
	s_addc_u32 s1, s21, 0
	v_lshlrev_b32_e32 v0, 1, v4
	v_ashrrev_i32_e32 v12, 2, v3
	v_lshl_add_u64 v[10:11], s[0:1], 0, v[0:1]
	s_mov_b64 s[0:1], 0x1eb00000
	s_lshl_b32 s20, s96, 2
	v_mul_lo_u32 v0, v6, s86
	v_and_b32_e32 v3, -16, v3
	s_lshl_b64 s[22:23], s[8:9], 6
	v_lshl_add_u64 v[50:51], v[10:11], 0, s[0:1]
	v_add3_u32 v67, v2, v0, v3
	v_mul_u32_u24_e32 v0, 0x90, v4
	s_add_u32 s0, s10, s20
	v_and_b32_e32 v44, -4, v12
	v_add_u32_e32 v41, v7, v9
	v_lshlrev_b32_e32 v7, 8, v42
	v_lshlrev_b32_e32 v8, 2, v4
	v_add3_u32 v68, v2, v0, v3
	s_addc_u32 s1, s11, 0
	v_mov_b32_e32 v9, v1
	s_movk_i32 s8, 0x48
	v_or_b32_e32 v0, 3, v12
	v_add_u32_e32 v65, v5, v7
	v_add3_u32 v66, v2, v8, s20
	v_add3_u32 v69, v2, s20, v8
	v_lshl_add_u64 v[52:53], s[0:1], 0, v[8:9]
	v_mad_u64_u32 v[8:9], s[0:1], v44, s8, v[6:7]
	v_mad_u64_u32 v[6:7], s[0:1], v0, s8, v[6:7]
	v_mov_b32_e32 v0, 0x300
	v_ashrrev_i32_e32 v45, 31, v44
	v_ashrrev_i32_e32 v43, 31, v42
	v_lshl_add_u32 v70, v8, 1, v2
	v_lshl_add_u32 v71, v6, 1, v2
	v_lshlrev_b32_e32 v72, 8, v44
	v_lshl_or_b32 v73, v12, 8, v0
	v_lshlrev_b32_e32 v54, 2, v4
	v_readlane_b32 s0, v254, 37
	s_branch .LBB0_634

; __device__ __forceinline__ bool xb_t0(int wave) { return wave == 0 && lane_id_asm() == 0; }
; __device__ __forceinline__ int launder_si(int v) { asm volatile("" : "+s"(v)); return v; }
; #define SEAM(k) do { if (IN(k) && IN((k) + 1)) xcd_barrier(bar); } while (0)
; __device__ __forceinline__ void xcd_barrier(const XcdBarrier& b) {
;     asm volatile("s_waitcnt vmcnt(0)" ::: "memory");
;     __syncthreads();
;     if (xb_t0(b.wave)) {
;         unsigned* bar = b.bar; unsigned bx = b.x;
;         asm volatile("" : "+s"(bar), "+s"(bx));
;         __builtin_amdgcn_s_waitcnt(0);
;         unsigned nloc = b.st[0], nx = b.st[1];
;         if (nloc == 0u) { xcd_barrier_complete(bar, bx, nloc, nx); b.st[0] = nloc; b.st[1] = nx; }
; __global__ void __launch_bounds__(NWAVES * 64, 2) trunk_fwd(Args args) {
;     ...
;         SEAM(s0 + 3);
;         if (IN(s0 + 4)) phase_scan2(F, launder_si(lq));
;         SEAM(s0 + 4);
.LBB0_714:
	s_setprio 0
	s_add_i32 s0, s61, 6
	s_cmp_ge_i32 s0, s51
	s_cbranch_scc1 .LBB0_762
	s_waitcnt vmcnt(0)
	v_cmp_ne_u32_e32 vcc, 1, v238
	s_waitcnt lgkmcnt(0)
	s_barrier
	s_cbranch_vccnz .LBB0_761
	v_mbcnt_lo_u32_b32 v0, -1, 0
	v_mbcnt_hi_u32_b32 v0, -1, v0
	s_nop 0
	v_cmp_eq_u32_e32 vcc, 0, v0
	s_and_saveexec_b64 s[38:39], vcc
	s_cbranch_execz .LBB0_760
	v_readlane_b32 s52, v254, 8
	v_readlane_b32 s6, v254, 11
	v_readlane_b32 s1, v254, 10
	v_readlane_b32 s53, v254, 9
	v_mov_b32_e32 v0, s6
	s_waitcnt vmcnt(0) expcnt(0) lgkmcnt(0)
	ds_read_b32 v2, v0
	ds_read_b32 v0, v0 offset:4
	s_waitcnt lgkmcnt(1)
	v_cmp_ne_u32_e32 vcc, 0, v2
	s_cbranch_vccnz .LBB0_731
	v_readlane_b32 s6, v254, 2
	v_readlane_b32 s7, v254, 3
	s_load_dwordx2 s[10:11], s[6:7], 0x4
	s_add_u32 s6, s52, 0x1000
	s_addc_u32 s7, s53, 0
	s_add_u32 s8, s52, 0x1100
	s_addc_u32 s9, s53, 0
	s_waitcnt lgkmcnt(0)
	s_mul_i32 s34, s10, s33
	s_add_u32 s10, s52, 0x1200
	s_mul_i32 s34, s34, s11
	s_addc_u32 s11, s53, 0
	s_add_u32 s12, s52, 0x1300
	s_addc_u32 s13, s53, 0
	s_mov_b32 s35, 1
	s_mov_b64 s[14:15], 0
	s_branch .LBB0_721
